# HGRN2 group body hand-scheduled (deferred output ops, 4-step double-buffered LDS fetch); SB attention loads hoisted; prep beta block vectorized
# speedup vs baseline: 1.0344x; 1.0167x over previous
.LBB0_819:
	v_add_u32_e32 v48, 0, v46
	v_add_u32_e32 v50, 0, v45
	v_add_u32_e32 v49, 0x1c000, v48
	v_add_u32_e32 v51, 0x1a200, v50
	v_add_u32_e32 v52, 0x1c200, v50
	v_add_u32_e32 v50, 0, v44
	v_add_u32_e32 v48, 0x1a000, v48
	v_add_u32_e32 v53, 0x12000, v50
	v_add_u32_e32 v54, 0x12080, v50
	v_add_u32_e32 v55, 0x12100, v50
	v_add_u32_e32 v56, 0x12180, v50
	ds_read_u16 v49, v49
	ds_read_u16 v51, v51
	ds_read_u16 v52, v52
	ds_read_u16 v116, v53
	ds_read_u16 v117, v54
	ds_read_u16 v118, v55
	ds_read_u16 v119, v56
	ds_read_u16 v48, v48
	s_waitcnt lgkmcnt(7)
	v_lshlrev_b32_e32 v49, 16, v49
	v_mul_f32_e64 v53, |v49|, s83
	v_exp_f32_e32 v53, v53
	v_cmp_le_f32_e32 vcc, 0, v49
	s_waitcnt lgkmcnt(0)
	v_lshlrev_b32_e32 v48, 16, v48
	v_lshlrev_b32_e32 v52, 16, v52
	v_add_f32_e32 v54, 1.0, v53
	v_rcp_f32_e32 v54, v54
	v_mul_f32_e64 v55, |v52|, s83
	v_exp_f32_e32 v55, v55
	v_lshlrev_b32_e32 v51, 16, v51
	v_mul_f32_e32 v53, v53, v54
	v_cndmask_b32_e32 v49, v53, v54, vcc
	v_mul_f32_e32 v54, 0xbfb8aa3b, v48
	v_exp_f32_e32 v54, v54
	v_mul_f32_e32 v57, 0xbfb8aa3b, v51
	v_exp_f32_e32 v57, v57
	v_add_f32_e32 v56, 1.0, v55
	v_add_f32_e32 v54, 1.0, v54
	v_rcp_f32_e32 v54, v54
	v_fma_f32 v49, v31, v49, v23
	v_add_u32_e32 v53, v30, v33
	v_rcp_f32_e32 v56, v56
	v_mul_f32_e32 v48, v54, v48
	ds_write2_b32 v53, v49, v48 offset1:4
	v_add_f32_e32 v49, 1.0, v57
	v_rcp_f32_e32 v49, v49
	v_mul_f32_e32 v48, v55, v56
	v_cmp_le_f32_e32 vcc, 0, v52
	v_add_u32_e32 v52, 0x12380, v50
	v_mul_f32_e32 v49, v49, v51
	v_cndmask_b32_e32 v48, v48, v56, vcc
	v_fma_f32 v48, v31, v48, v23
	ds_write2_b32 v37, v48, v49 offset1:4
	v_mov_b32_e32 v124, s18
	v_add_u32_e32 v125, 0x12000, v50
	v_lshl_add_u32 v51, s40, 15, v34
	ds_read_b128 v[52:55], v124 offset:0
	ds_read_b128 v[56:59], v124 offset:16
	ds_read_b128 v[60:63], v124 offset:32
	ds_read_b128 v[64:67], v124 offset:48
	ds_read_b128 v[68:71], v124 offset:64
	ds_read_b128 v[72:75], v124 offset:80
	ds_read_b128 v[76:79], v124 offset:96
	ds_read_b128 v[80:83], v124 offset:112
	s_waitcnt lgkmcnt(0)
	v_lshlrev_b32_e32 v126, 16, v116
	v_pk_add_f32 v[130:131], v[26:27], v[126:127] op_sel_hi:[1,0] neg_lo:[0,1] neg_hi:[0,1]
	v_pk_add_f32 v[132:133], v[24:25], v[126:127] op_sel_hi:[1,0] neg_lo:[0,1] neg_hi:[0,1]
	v_lshlrev_b32_e32 v128, 16, v117
	v_pk_fma_f32 v[26:27], v[130:131], v[52:53], v[126:127] op_sel_hi:[1,1,0]
	v_pk_fma_f32 v[24:25], v[132:133], v[54:55], v[126:127] op_sel_hi:[1,1,0]
	ds_read_u16 v120, v125 offset:512
	ds_read_u16 v121, v125 offset:640
	ds_read_u16 v122, v125 offset:768
	ds_read_u16 v123, v125 offset:896
	ds_read_b128 v[84:87], v124 offset:128
	ds_read_b128 v[88:91], v124 offset:144
	ds_read_b128 v[92:95], v124 offset:160
	ds_read_b128 v[96:99], v124 offset:176
	ds_read_b128 v[100:103], v124 offset:192
	ds_read_b128 v[104:107], v124 offset:208
	ds_read_b128 v[108:111], v124 offset:224
	ds_read_b128 v[112:115], v124 offset:240
	v_pk_mul_f32 v[134:135], v[58:59], v[24:25]
	v_pk_add_f32 v[130:131], v[26:27], v[128:129] op_sel_hi:[1,0] neg_lo:[0,1] neg_hi:[0,1]
	v_pk_add_f32 v[132:133], v[24:25], v[128:129] op_sel_hi:[1,0] neg_lo:[0,1] neg_hi:[0,1]
	v_lshlrev_b32_e32 v126, 16, v118
	v_pk_fma_f32 v[134:135], v[56:57], v[26:27], v[134:135]
	v_pk_fma_f32 v[26:27], v[130:131], v[60:61], v[128:129] op_sel_hi:[1,1,0]
	v_pk_fma_f32 v[24:25], v[132:133], v[62:63], v[128:129] op_sel_hi:[1,1,0]
	v_add_f32_e32 v136, v134, v135
	v_pk_mul_f32 v[134:135], v[66:67], v[24:25]
	v_pk_add_f32 v[130:131], v[26:27], v[126:127] op_sel_hi:[1,0] neg_lo:[0,1] neg_hi:[0,1]
	v_pk_add_f32 v[132:133], v[24:25], v[126:127] op_sel_hi:[1,0] neg_lo:[0,1] neg_hi:[0,1]
	v_lshlrev_b32_e32 v128, 16, v119
	v_pk_fma_f32 v[134:135], v[64:65], v[26:27], v[134:135]
	v_pk_fma_f32 v[26:27], v[130:131], v[68:69], v[126:127] op_sel_hi:[1,1,0]
	v_pk_fma_f32 v[24:25], v[132:133], v[70:71], v[126:127] op_sel_hi:[1,1,0]
	v_add_f32_e32 v137, v134, v135
	ds_write2st64_b32 v51, v136, v137 offset0:32 offset1:33
	v_pk_mul_f32 v[134:135], v[74:75], v[24:25]
	v_pk_add_f32 v[130:131], v[26:27], v[128:129] op_sel_hi:[1,0] neg_lo:[0,1] neg_hi:[0,1]
	v_pk_add_f32 v[132:133], v[24:25], v[128:129] op_sel_hi:[1,0] neg_lo:[0,1] neg_hi:[0,1]
	v_pk_fma_f32 v[134:135], v[72:73], v[26:27], v[134:135]
	v_pk_fma_f32 v[26:27], v[130:131], v[76:77], v[128:129] op_sel_hi:[1,1,0]
	v_pk_fma_f32 v[24:25], v[132:133], v[78:79], v[128:129] op_sel_hi:[1,1,0]
	v_add_f32_e32 v138, v134, v135
	s_waitcnt lgkmcnt(1)
	v_lshlrev_b32_e32 v126, 16, v120
	v_pk_mul_f32 v[134:135], v[82:83], v[24:25]
	v_pk_add_f32 v[130:131], v[26:27], v[126:127] op_sel_hi:[1,0] neg_lo:[0,1] neg_hi:[0,1]
	v_pk_add_f32 v[132:133], v[24:25], v[126:127] op_sel_hi:[1,0] neg_lo:[0,1] neg_hi:[0,1]
	v_lshlrev_b32_e32 v128, 16, v121
	v_pk_fma_f32 v[134:135], v[80:81], v[26:27], v[134:135]
	v_pk_fma_f32 v[26:27], v[130:131], v[84:85], v[126:127] op_sel_hi:[1,1,0]
	v_pk_fma_f32 v[24:25], v[132:133], v[86:87], v[126:127] op_sel_hi:[1,1,0]
	v_add_f32_e32 v139, v134, v135
	ds_write2st64_b32 v51, v138, v139 offset0:34 offset1:35
	ds_read_u16 v116, v125 offset:1024
	ds_read_u16 v117, v125 offset:1152
	ds_read_u16 v118, v125 offset:1280
	ds_read_u16 v119, v125 offset:1408
	ds_read_b128 v[52:55], v124 offset:256
	ds_read_b128 v[56:59], v124 offset:272
	ds_read_b128 v[60:63], v124 offset:288
	ds_read_b128 v[64:67], v124 offset:304
	ds_read_b128 v[68:71], v124 offset:320
	ds_read_b128 v[72:75], v124 offset:336
	ds_read_b128 v[76:79], v124 offset:352
	ds_read_b128 v[80:83], v124 offset:368
	v_pk_mul_f32 v[134:135], v[90:91], v[24:25]
	v_pk_add_f32 v[130:131], v[26:27], v[128:129] op_sel_hi:[1,0] neg_lo:[0,1] neg_hi:[0,1]
	v_pk_add_f32 v[132:133], v[24:25], v[128:129] op_sel_hi:[1,0] neg_lo:[0,1] neg_hi:[0,1]
	v_lshlrev_b32_e32 v126, 16, v122
	v_pk_fma_f32 v[134:135], v[88:89], v[26:27], v[134:135]
	v_pk_fma_f32 v[26:27], v[130:131], v[92:93], v[128:129] op_sel_hi:[1,1,0]
	v_pk_fma_f32 v[24:25], v[132:133], v[94:95], v[128:129] op_sel_hi:[1,1,0]
	v_add_f32_e32 v136, v134, v135
	v_pk_mul_f32 v[134:135], v[98:99], v[24:25]
	v_pk_add_f32 v[130:131], v[26:27], v[126:127] op_sel_hi:[1,0] neg_lo:[0,1] neg_hi:[0,1]
	v_pk_add_f32 v[132:133], v[24:25], v[126:127] op_sel_hi:[1,0] neg_lo:[0,1] neg_hi:[0,1]
	v_lshlrev_b32_e32 v128, 16, v123
	v_pk_fma_f32 v[134:135], v[96:97], v[26:27], v[134:135]
	v_pk_fma_f32 v[26:27], v[130:131], v[100:101], v[126:127] op_sel_hi:[1,1,0]
	v_pk_fma_f32 v[24:25], v[132:133], v[102:103], v[126:127] op_sel_hi:[1,1,0]
	v_add_f32_e32 v137, v134, v135
	ds_write2st64_b32 v51, v136, v137 offset0:36 offset1:37
	v_pk_mul_f32 v[134:135], v[106:107], v[24:25]
	v_pk_add_f32 v[130:131], v[26:27], v[128:129] op_sel_hi:[1,0] neg_lo:[0,1] neg_hi:[0,1]
	v_pk_add_f32 v[132:133], v[24:25], v[128:129] op_sel_hi:[1,0] neg_lo:[0,1] neg_hi:[0,1]
	v_pk_fma_f32 v[134:135], v[104:105], v[26:27], v[134:135]
	v_pk_fma_f32 v[26:27], v[130:131], v[108:109], v[128:129] op_sel_hi:[1,1,0]
	v_pk_fma_f32 v[24:25], v[132:133], v[110:111], v[128:129] op_sel_hi:[1,1,0]
	v_add_f32_e32 v138, v134, v135
	s_waitcnt lgkmcnt(1)
	v_lshlrev_b32_e32 v126, 16, v116
	v_pk_mul_f32 v[134:135], v[114:115], v[24:25]
	v_pk_add_f32 v[130:131], v[26:27], v[126:127] op_sel_hi:[1,0] neg_lo:[0,1] neg_hi:[0,1]
	v_pk_add_f32 v[132:133], v[24:25], v[126:127] op_sel_hi:[1,0] neg_lo:[0,1] neg_hi:[0,1]
	v_lshlrev_b32_e32 v128, 16, v117
	v_pk_fma_f32 v[134:135], v[112:113], v[26:27], v[134:135]
	v_pk_fma_f32 v[26:27], v[130:131], v[52:53], v[126:127] op_sel_hi:[1,1,0]
	v_pk_fma_f32 v[24:25], v[132:133], v[54:55], v[126:127] op_sel_hi:[1,1,0]
	v_add_f32_e32 v139, v134, v135
	ds_write2st64_b32 v51, v138, v139 offset0:38 offset1:39
	ds_read_u16 v120, v125 offset:1536
	ds_read_u16 v121, v125 offset:1664
	ds_read_u16 v122, v125 offset:1792
	ds_read_u16 v123, v125 offset:1920
	ds_read_b128 v[84:87], v124 offset:384
	ds_read_b128 v[88:91], v124 offset:400
	ds_read_b128 v[92:95], v124 offset:416
	ds_read_b128 v[96:99], v124 offset:432
	ds_read_b128 v[100:103], v124 offset:448
	ds_read_b128 v[104:107], v124 offset:464
	ds_read_b128 v[108:111], v124 offset:480
	ds_read_b128 v[112:115], v124 offset:496
	v_pk_mul_f32 v[134:135], v[58:59], v[24:25]
	v_pk_add_f32 v[130:131], v[26:27], v[128:129] op_sel_hi:[1,0] neg_lo:[0,1] neg_hi:[0,1]
	v_pk_add_f32 v[132:133], v[24:25], v[128:129] op_sel_hi:[1,0] neg_lo:[0,1] neg_hi:[0,1]
	v_lshlrev_b32_e32 v126, 16, v118
	v_pk_fma_f32 v[134:135], v[56:57], v[26:27], v[134:135]
	v_pk_fma_f32 v[26:27], v[130:131], v[60:61], v[128:129] op_sel_hi:[1,1,0]
	v_pk_fma_f32 v[24:25], v[132:133], v[62:63], v[128:129] op_sel_hi:[1,1,0]
	v_add_f32_e32 v136, v134, v135
	v_pk_mul_f32 v[134:135], v[66:67], v[24:25]
	v_pk_add_f32 v[130:131], v[26:27], v[126:127] op_sel_hi:[1,0] neg_lo:[0,1] neg_hi:[0,1]
	v_pk_add_f32 v[132:133], v[24:25], v[126:127] op_sel_hi:[1,0] neg_lo:[0,1] neg_hi:[0,1]
	v_lshlrev_b32_e32 v128, 16, v119
	v_pk_fma_f32 v[134:135], v[64:65], v[26:27], v[134:135]
	v_pk_fma_f32 v[26:27], v[130:131], v[68:69], v[126:127] op_sel_hi:[1,1,0]
	v_pk_fma_f32 v[24:25], v[132:133], v[70:71], v[126:127] op_sel_hi:[1,1,0]
	v_add_f32_e32 v137, v134, v135
	ds_write2st64_b32 v51, v136, v137 offset0:40 offset1:41
	v_pk_mul_f32 v[134:135], v[74:75], v[24:25]
	v_pk_add_f32 v[130:131], v[26:27], v[128:129] op_sel_hi:[1,0] neg_lo:[0,1] neg_hi:[0,1]
	v_pk_add_f32 v[132:133], v[24:25], v[128:129] op_sel_hi:[1,0] neg_lo:[0,1] neg_hi:[0,1]
	v_pk_fma_f32 v[134:135], v[72:73], v[26:27], v[134:135]
	v_pk_fma_f32 v[26:27], v[130:131], v[76:77], v[128:129] op_sel_hi:[1,1,0]
	v_pk_fma_f32 v[24:25], v[132:133], v[78:79], v[128:129] op_sel_hi:[1,1,0]
	v_add_f32_e32 v138, v134, v135
	s_waitcnt lgkmcnt(1)
	v_lshlrev_b32_e32 v126, 16, v120
	v_pk_mul_f32 v[134:135], v[82:83], v[24:25]
	v_pk_add_f32 v[130:131], v[26:27], v[126:127] op_sel_hi:[1,0] neg_lo:[0,1] neg_hi:[0,1]
	v_pk_add_f32 v[132:133], v[24:25], v[126:127] op_sel_hi:[1,0] neg_lo:[0,1] neg_hi:[0,1]
	v_lshlrev_b32_e32 v128, 16, v121
	v_pk_fma_f32 v[134:135], v[80:81], v[26:27], v[134:135]
	v_pk_fma_f32 v[26:27], v[130:131], v[84:85], v[126:127] op_sel_hi:[1,1,0]
	v_pk_fma_f32 v[24:25], v[132:133], v[86:87], v[126:127] op_sel_hi:[1,1,0]
	v_add_f32_e32 v139, v134, v135
	ds_write2st64_b32 v51, v138, v139 offset0:42 offset1:43
	ds_read_u16 v116, v125 offset:2048
	ds_read_u16 v117, v125 offset:2176
	ds_read_u16 v118, v125 offset:2304
	ds_read_u16 v119, v125 offset:2432
	ds_read_b128 v[52:55], v124 offset:512
	ds_read_b128 v[56:59], v124 offset:528
	ds_read_b128 v[60:63], v124 offset:544
	ds_read_b128 v[64:67], v124 offset:560
	ds_read_b128 v[68:71], v124 offset:576
	ds_read_b128 v[72:75], v124 offset:592
	ds_read_b128 v[76:79], v124 offset:608
	ds_read_b128 v[80:83], v124 offset:624
	v_pk_mul_f32 v[134:135], v[90:91], v[24:25]
	v_pk_add_f32 v[130:131], v[26:27], v[128:129] op_sel_hi:[1,0] neg_lo:[0,1] neg_hi:[0,1]
	v_pk_add_f32 v[132:133], v[24:25], v[128:129] op_sel_hi:[1,0] neg_lo:[0,1] neg_hi:[0,1]
	v_lshlrev_b32_e32 v126, 16, v122
	v_pk_fma_f32 v[134:135], v[88:89], v[26:27], v[134:135]
	v_pk_fma_f32 v[26:27], v[130:131], v[92:93], v[128:129] op_sel_hi:[1,1,0]
	v_pk_fma_f32 v[24:25], v[132:133], v[94:95], v[128:129] op_sel_hi:[1,1,0]
	v_add_f32_e32 v136, v134, v135
	v_pk_mul_f32 v[134:135], v[98:99], v[24:25]
	v_pk_add_f32 v[130:131], v[26:27], v[126:127] op_sel_hi:[1,0] neg_lo:[0,1] neg_hi:[0,1]
	v_pk_add_f32 v[132:133], v[24:25], v[126:127] op_sel_hi:[1,0] neg_lo:[0,1] neg_hi:[0,1]
	v_lshlrev_b32_e32 v128, 16, v123
	v_pk_fma_f32 v[134:135], v[96:97], v[26:27], v[134:135]
	v_pk_fma_f32 v[26:27], v[130:131], v[100:101], v[126:127] op_sel_hi:[1,1,0]
	v_pk_fma_f32 v[24:25], v[132:133], v[102:103], v[126:127] op_sel_hi:[1,1,0]
	v_add_f32_e32 v137, v134, v135
	ds_write2st64_b32 v51, v136, v137 offset0:44 offset1:45
	v_pk_mul_f32 v[134:135], v[106:107], v[24:25]
	v_pk_add_f32 v[130:131], v[26:27], v[128:129] op_sel_hi:[1,0] neg_lo:[0,1] neg_hi:[0,1]
	v_pk_add_f32 v[132:133], v[24:25], v[128:129] op_sel_hi:[1,0] neg_lo:[0,1] neg_hi:[0,1]
	v_pk_fma_f32 v[134:135], v[104:105], v[26:27], v[134:135]
	v_pk_fma_f32 v[26:27], v[130:131], v[108:109], v[128:129] op_sel_hi:[1,1,0]
	v_pk_fma_f32 v[24:25], v[132:133], v[110:111], v[128:129] op_sel_hi:[1,1,0]
	v_add_f32_e32 v138, v134, v135
	s_waitcnt lgkmcnt(1)
	v_lshlrev_b32_e32 v126, 16, v116
	v_pk_mul_f32 v[134:135], v[114:115], v[24:25]
	v_pk_add_f32 v[130:131], v[26:27], v[126:127] op_sel_hi:[1,0] neg_lo:[0,1] neg_hi:[0,1]
	v_pk_add_f32 v[132:133], v[24:25], v[126:127] op_sel_hi:[1,0] neg_lo:[0,1] neg_hi:[0,1]
	v_lshlrev_b32_e32 v128, 16, v117
	v_pk_fma_f32 v[134:135], v[112:113], v[26:27], v[134:135]
	v_pk_fma_f32 v[26:27], v[130:131], v[52:53], v[126:127] op_sel_hi:[1,1,0]
	v_pk_fma_f32 v[24:25], v[132:133], v[54:55], v[126:127] op_sel_hi:[1,1,0]
	v_add_f32_e32 v139, v134, v135
	ds_write2st64_b32 v51, v138, v139 offset0:46 offset1:47
	ds_read_u16 v120, v125 offset:2560
	ds_read_u16 v121, v125 offset:2688
	ds_read_u16 v122, v125 offset:2816
	ds_read_u16 v123, v125 offset:2944
	ds_read_b128 v[84:87], v124 offset:640
	ds_read_b128 v[88:91], v124 offset:656
	ds_read_b128 v[92:95], v124 offset:672
	ds_read_b128 v[96:99], v124 offset:688
	ds_read_b128 v[100:103], v124 offset:704
	ds_read_b128 v[104:107], v124 offset:720
	ds_read_b128 v[108:111], v124 offset:736
	ds_read_b128 v[112:115], v124 offset:752
	v_pk_mul_f32 v[134:135], v[58:59], v[24:25]
	v_pk_add_f32 v[130:131], v[26:27], v[128:129] op_sel_hi:[1,0] neg_lo:[0,1] neg_hi:[0,1]
	v_pk_add_f32 v[132:133], v[24:25], v[128:129] op_sel_hi:[1,0] neg_lo:[0,1] neg_hi:[0,1]
	v_lshlrev_b32_e32 v126, 16, v118
	v_pk_fma_f32 v[134:135], v[56:57], v[26:27], v[134:135]
	v_pk_fma_f32 v[26:27], v[130:131], v[60:61], v[128:129] op_sel_hi:[1,1,0]
	v_pk_fma_f32 v[24:25], v[132:133], v[62:63], v[128:129] op_sel_hi:[1,1,0]
	v_add_f32_e32 v136, v134, v135
	v_pk_mul_f32 v[134:135], v[66:67], v[24:25]
	v_pk_add_f32 v[130:131], v[26:27], v[126:127] op_sel_hi:[1,0] neg_lo:[0,1] neg_hi:[0,1]
	v_pk_add_f32 v[132:133], v[24:25], v[126:127] op_sel_hi:[1,0] neg_lo:[0,1] neg_hi:[0,1]
	v_lshlrev_b32_e32 v128, 16, v119
	v_pk_fma_f32 v[134:135], v[64:65], v[26:27], v[134:135]
	v_pk_fma_f32 v[26:27], v[130:131], v[68:69], v[126:127] op_sel_hi:[1,1,0]
	v_pk_fma_f32 v[24:25], v[132:133], v[70:71], v[126:127] op_sel_hi:[1,1,0]
	v_add_f32_e32 v137, v134, v135
	ds_write2st64_b32 v51, v136, v137 offset0:48 offset1:49
	v_pk_mul_f32 v[134:135], v[74:75], v[24:25]
	v_pk_add_f32 v[130:131], v[26:27], v[128:129] op_sel_hi:[1,0] neg_lo:[0,1] neg_hi:[0,1]
	v_pk_add_f32 v[132:133], v[24:25], v[128:129] op_sel_hi:[1,0] neg_lo:[0,1] neg_hi:[0,1]
	v_pk_fma_f32 v[134:135], v[72:73], v[26:27], v[134:135]
	v_pk_fma_f32 v[26:27], v[130:131], v[76:77], v[128:129] op_sel_hi:[1,1,0]
	v_pk_fma_f32 v[24:25], v[132:133], v[78:79], v[128:129] op_sel_hi:[1,1,0]
	v_add_f32_e32 v138, v134, v135
	s_waitcnt lgkmcnt(1)
	v_lshlrev_b32_e32 v126, 16, v120
	v_pk_mul_f32 v[134:135], v[82:83], v[24:25]
	v_pk_add_f32 v[130:131], v[26:27], v[126:127] op_sel_hi:[1,0] neg_lo:[0,1] neg_hi:[0,1]
	v_pk_add_f32 v[132:133], v[24:25], v[126:127] op_sel_hi:[1,0] neg_lo:[0,1] neg_hi:[0,1]
	v_lshlrev_b32_e32 v128, 16, v121
	v_pk_fma_f32 v[134:135], v[80:81], v[26:27], v[134:135]
	v_pk_fma_f32 v[26:27], v[130:131], v[84:85], v[126:127] op_sel_hi:[1,1,0]
	v_pk_fma_f32 v[24:25], v[132:133], v[86:87], v[126:127] op_sel_hi:[1,1,0]
	v_add_f32_e32 v139, v134, v135
	ds_write2st64_b32 v51, v138, v139 offset0:50 offset1:51
	ds_read_u16 v116, v125 offset:3072
	ds_read_u16 v117, v125 offset:3200
	ds_read_u16 v118, v125 offset:3328
	ds_read_u16 v119, v125 offset:3456
	ds_read_b128 v[52:55], v124 offset:768
	ds_read_b128 v[56:59], v124 offset:784
	ds_read_b128 v[60:63], v124 offset:800
	ds_read_b128 v[64:67], v124 offset:816
	ds_read_b128 v[68:71], v124 offset:832
	ds_read_b128 v[72:75], v124 offset:848
	ds_read_b128 v[76:79], v124 offset:864
	ds_read_b128 v[80:83], v124 offset:880
	v_pk_mul_f32 v[134:135], v[90:91], v[24:25]
	v_pk_add_f32 v[130:131], v[26:27], v[128:129] op_sel_hi:[1,0] neg_lo:[0,1] neg_hi:[0,1]
	v_pk_add_f32 v[132:133], v[24:25], v[128:129] op_sel_hi:[1,0] neg_lo:[0,1] neg_hi:[0,1]
	v_lshlrev_b32_e32 v126, 16, v122
	v_pk_fma_f32 v[134:135], v[88:89], v[26:27], v[134:135]
	v_pk_fma_f32 v[26:27], v[130:131], v[92:93], v[128:129] op_sel_hi:[1,1,0]
	v_pk_fma_f32 v[24:25], v[132:133], v[94:95], v[128:129] op_sel_hi:[1,1,0]
	v_add_f32_e32 v136, v134, v135
	v_pk_mul_f32 v[134:135], v[98:99], v[24:25]
	v_pk_add_f32 v[130:131], v[26:27], v[126:127] op_sel_hi:[1,0] neg_lo:[0,1] neg_hi:[0,1]
	v_pk_add_f32 v[132:133], v[24:25], v[126:127] op_sel_hi:[1,0] neg_lo:[0,1] neg_hi:[0,1]
	v_lshlrev_b32_e32 v128, 16, v123
	v_pk_fma_f32 v[134:135], v[96:97], v[26:27], v[134:135]
	v_pk_fma_f32 v[26:27], v[130:131], v[100:101], v[126:127] op_sel_hi:[1,1,0]
	v_pk_fma_f32 v[24:25], v[132:133], v[102:103], v[126:127] op_sel_hi:[1,1,0]
	v_add_f32_e32 v137, v134, v135
	ds_write2st64_b32 v51, v136, v137 offset0:52 offset1:53
	v_pk_mul_f32 v[134:135], v[106:107], v[24:25]
	v_pk_add_f32 v[130:131], v[26:27], v[128:129] op_sel_hi:[1,0] neg_lo:[0,1] neg_hi:[0,1]
	v_pk_add_f32 v[132:133], v[24:25], v[128:129] op_sel_hi:[1,0] neg_lo:[0,1] neg_hi:[0,1]
	v_pk_fma_f32 v[134:135], v[104:105], v[26:27], v[134:135]
	v_pk_fma_f32 v[26:27], v[130:131], v[108:109], v[128:129] op_sel_hi:[1,1,0]
	v_pk_fma_f32 v[24:25], v[132:133], v[110:111], v[128:129] op_sel_hi:[1,1,0]
	v_add_f32_e32 v138, v134, v135
	s_waitcnt lgkmcnt(1)
	v_lshlrev_b32_e32 v126, 16, v116
	v_pk_mul_f32 v[134:135], v[114:115], v[24:25]
	v_pk_add_f32 v[130:131], v[26:27], v[126:127] op_sel_hi:[1,0] neg_lo:[0,1] neg_hi:[0,1]
	v_pk_add_f32 v[132:133], v[24:25], v[126:127] op_sel_hi:[1,0] neg_lo:[0,1] neg_hi:[0,1]
	v_lshlrev_b32_e32 v128, 16, v117
	v_pk_fma_f32 v[134:135], v[112:113], v[26:27], v[134:135]
	v_pk_fma_f32 v[26:27], v[130:131], v[52:53], v[126:127] op_sel_hi:[1,1,0]
	v_pk_fma_f32 v[24:25], v[132:133], v[54:55], v[126:127] op_sel_hi:[1,1,0]
	v_add_f32_e32 v139, v134, v135
	ds_write2st64_b32 v51, v138, v139 offset0:54 offset1:55
	ds_read_u16 v120, v125 offset:3584
	ds_read_u16 v121, v125 offset:3712
	ds_read_u16 v122, v125 offset:3840
	ds_read_u16 v123, v125 offset:3968
	ds_read_b128 v[84:87], v124 offset:896
	ds_read_b128 v[88:91], v124 offset:912
	ds_read_b128 v[92:95], v124 offset:928
	ds_read_b128 v[96:99], v124 offset:944
	ds_read_b128 v[100:103], v124 offset:960
	ds_read_b128 v[104:107], v124 offset:976
	ds_read_b128 v[108:111], v124 offset:992
	ds_read_b128 v[112:115], v124 offset:1008
	v_pk_mul_f32 v[134:135], v[58:59], v[24:25]
	v_pk_add_f32 v[130:131], v[26:27], v[128:129] op_sel_hi:[1,0] neg_lo:[0,1] neg_hi:[0,1]
	v_pk_add_f32 v[132:133], v[24:25], v[128:129] op_sel_hi:[1,0] neg_lo:[0,1] neg_hi:[0,1]
	v_lshlrev_b32_e32 v126, 16, v118
	v_pk_fma_f32 v[134:135], v[56:57], v[26:27], v[134:135]
	v_pk_fma_f32 v[26:27], v[130:131], v[60:61], v[128:129] op_sel_hi:[1,1,0]
	v_pk_fma_f32 v[24:25], v[132:133], v[62:63], v[128:129] op_sel_hi:[1,1,0]
	v_add_f32_e32 v136, v134, v135
	v_pk_mul_f32 v[134:135], v[66:67], v[24:25]
	v_pk_add_f32 v[130:131], v[26:27], v[126:127] op_sel_hi:[1,0] neg_lo:[0,1] neg_hi:[0,1]
	v_pk_add_f32 v[132:133], v[24:25], v[126:127] op_sel_hi:[1,0] neg_lo:[0,1] neg_hi:[0,1]
	v_lshlrev_b32_e32 v128, 16, v119
	v_pk_fma_f32 v[134:135], v[64:65], v[26:27], v[134:135]
	v_pk_fma_f32 v[26:27], v[130:131], v[68:69], v[126:127] op_sel_hi:[1,1,0]
	v_pk_fma_f32 v[24:25], v[132:133], v[70:71], v[126:127] op_sel_hi:[1,1,0]
	v_add_f32_e32 v137, v134, v135
	ds_write2st64_b32 v51, v136, v137 offset0:56 offset1:57
	v_pk_mul_f32 v[134:135], v[74:75], v[24:25]
	v_pk_add_f32 v[130:131], v[26:27], v[128:129] op_sel_hi:[1,0] neg_lo:[0,1] neg_hi:[0,1]
	v_pk_add_f32 v[132:133], v[24:25], v[128:129] op_sel_hi:[1,0] neg_lo:[0,1] neg_hi:[0,1]
	v_pk_fma_f32 v[134:135], v[72:73], v[26:27], v[134:135]
	v_pk_fma_f32 v[26:27], v[130:131], v[76:77], v[128:129] op_sel_hi:[1,1,0]
	v_pk_fma_f32 v[24:25], v[132:133], v[78:79], v[128:129] op_sel_hi:[1,1,0]
	v_add_f32_e32 v138, v134, v135
	s_waitcnt lgkmcnt(1)
	v_lshlrev_b32_e32 v126, 16, v120
	v_pk_mul_f32 v[134:135], v[82:83], v[24:25]
	v_pk_add_f32 v[130:131], v[26:27], v[126:127] op_sel_hi:[1,0] neg_lo:[0,1] neg_hi:[0,1]
	v_pk_add_f32 v[132:133], v[24:25], v[126:127] op_sel_hi:[1,0] neg_lo:[0,1] neg_hi:[0,1]
	v_lshlrev_b32_e32 v128, 16, v121
	v_pk_fma_f32 v[134:135], v[80:81], v[26:27], v[134:135]
	v_pk_fma_f32 v[26:27], v[130:131], v[84:85], v[126:127] op_sel_hi:[1,1,0]
	v_pk_fma_f32 v[24:25], v[132:133], v[86:87], v[126:127] op_sel_hi:[1,1,0]
	v_add_f32_e32 v139, v134, v135
	ds_write2st64_b32 v51, v138, v139 offset0:58 offset1:59
	v_pk_mul_f32 v[134:135], v[90:91], v[24:25]
	v_pk_add_f32 v[130:131], v[26:27], v[128:129] op_sel_hi:[1,0] neg_lo:[0,1] neg_hi:[0,1]
	v_pk_add_f32 v[132:133], v[24:25], v[128:129] op_sel_hi:[1,0] neg_lo:[0,1] neg_hi:[0,1]
	v_lshlrev_b32_e32 v126, 16, v122
	v_pk_fma_f32 v[134:135], v[88:89], v[26:27], v[134:135]
	v_pk_fma_f32 v[26:27], v[130:131], v[92:93], v[128:129] op_sel_hi:[1,1,0]
	v_pk_fma_f32 v[24:25], v[132:133], v[94:95], v[128:129] op_sel_hi:[1,1,0]
	v_add_f32_e32 v136, v134, v135
	v_pk_mul_f32 v[134:135], v[98:99], v[24:25]
	v_pk_add_f32 v[130:131], v[26:27], v[126:127] op_sel_hi:[1,0] neg_lo:[0,1] neg_hi:[0,1]
	v_pk_add_f32 v[132:133], v[24:25], v[126:127] op_sel_hi:[1,0] neg_lo:[0,1] neg_hi:[0,1]
	v_lshlrev_b32_e32 v128, 16, v123
	v_pk_fma_f32 v[134:135], v[96:97], v[26:27], v[134:135]
	v_pk_fma_f32 v[26:27], v[130:131], v[100:101], v[126:127] op_sel_hi:[1,1,0]
	v_pk_fma_f32 v[24:25], v[132:133], v[102:103], v[126:127] op_sel_hi:[1,1,0]
	v_add_f32_e32 v137, v134, v135
	ds_write2st64_b32 v51, v136, v137 offset0:60 offset1:61
	v_pk_mul_f32 v[134:135], v[106:107], v[24:25]
	v_pk_add_f32 v[130:131], v[26:27], v[128:129] op_sel_hi:[1,0] neg_lo:[0,1] neg_hi:[0,1]
	v_pk_add_f32 v[132:133], v[24:25], v[128:129] op_sel_hi:[1,0] neg_lo:[0,1] neg_hi:[0,1]
	v_pk_fma_f32 v[134:135], v[104:105], v[26:27], v[134:135]
	v_pk_fma_f32 v[26:27], v[130:131], v[108:109], v[128:129] op_sel_hi:[1,1,0]
	v_pk_fma_f32 v[24:25], v[132:133], v[110:111], v[128:129] op_sel_hi:[1,1,0]
	v_add_f32_e32 v138, v134, v135
	v_pk_mul_f32 v[134:135], v[114:115], v[24:25]
	s_nop 0
	v_pk_fma_f32 v[134:135], v[112:113], v[26:27], v[134:135]
	s_nop 0
	v_add_f32_e32 v139, v134, v135
	ds_write2st64_b32 v51, v138, v139 offset0:62 offset1:63

.LBB0_844:
	s_mov_b32 s59, s45
	v_lshl_add_u64 v[24:25], v[44:45], 0, s[58:59]
	v_mov_b64_e32 v[26:27], s[20:21]
	v_mad_u64_u32 v[26:27], s[10:11], v24, s90, v[26:27]
	v_mad_i32_i24 v27, v25, s90, v27
	s_lshl_b32 s44, s46, 1
	v_lshl_add_u64 v[24:25], v[26:27], 0, s[44:45]
	v_lshl_add_u64 v[48:49], v[24:25], 0, v[156:157]
	v_add_co_u32_e32 v24, vcc, s76, v48
	s_mov_b64 s[10:11], 0x1e200
	s_nop 0
	v_addc_co_u32_e32 v25, vcc, 0, v49, vcc
	global_load_dwordx4 v[24:27], v[24:25], off offset:512
	v_lshl_add_u64 v[30:31], v[48:49], 0, s[10:11]
	global_load_dwordx4 v[52:55], v[30:31], off offset:64
	global_load_dwordx4 v[58:61], v[48:49], off offset:576
	global_load_dwordx4 v[96:99], v[48:49], off offset:512
	v_lshl_add_u64 v[116:117], s[58:59], 1, v[46:47]
	global_load_dwordx2 v[100:101], v[116:117], off
	global_load_dwordx2 v[102:103], v[116:117], off offset:32
	v_add_co_u32_e32 v118, vcc, s79, v116
	s_nop 1
	v_addc_co_u32_e32 v119, vcc, 0, v117, vcc
	global_load_dwordx2 v[104:105], v[118:119], off
	global_load_dwordx2 v[106:107], v[118:119], off offset:32
	v_add_co_u32_e32 v118, vcc, s91, v116
	s_nop 1
	v_addc_co_u32_e32 v119, vcc, 0, v117, vcc
	global_load_dwordx2 v[108:109], v[118:119], off
	global_load_dwordx2 v[110:111], v[118:119], off offset:32
	v_add_co_u32_e32 v118, vcc, s92, v116
	s_nop 1
	v_addc_co_u32_e32 v119, vcc, 0, v117, vcc
	global_load_dwordx2 v[112:113], v[118:119], off
	global_load_dwordx2 v[114:115], v[118:119], off offset:32
	v_add_u32_e32 v29, s58, v36
	v_add_u32_e32 v30, 16, v29
	v_cmp_lt_u32_e32 vcc, v30, v33
	s_waitcnt vmcnt(11)
	v_mfma_f32_16x16x32_bf16 v[24:27], v[24:27], v[16:19], 0
	s_waitcnt vmcnt(10)
	v_mfma_f32_16x16x32_bf16 v[24:27], v[52:55], v[20:23], v[24:27]
	s_nop 7
	v_mul_f32_e32 v31, 0x3e000000, v24
	v_max_f32_e32 v30, 0, v31
	v_mul_f32_e64 v31, |v31|, s83
	v_exp_f32_e32 v31, v31
	s_nop 0
	v_add_f32_e32 v31, 1.0, v31
	v_cmp_gt_f32_e64 s[10:11], s93, v31
	s_nop 1
	v_cndmask_b32_e64 v52, 0, 32, s[10:11]
	v_ldexp_f32 v31, v31, v52
	v_log_f32_e32 v31, v31
	s_nop 0
	v_mul_f32_e32 v52, 0x3f317217, v31
	v_fma_f32 v52, v31, s96, -v52
	v_fmac_f32_e32 v52, 0x3377d1cf, v31
	v_fmac_f32_e32 v52, 0x3f317217, v31
	v_cmp_lt_f32_e64 s[12:13], |v31|, s77
	s_nop 1
	v_cndmask_b32_e64 v31, v31, v52, s[12:13]
	v_cndmask_b32_e64 v52, 0, v224, s[10:11]
	v_sub_f32_e32 v31, v31, v52
	v_add_f32_e32 v30, v30, v31
	v_cndmask_b32_e64 v31, 0, -v30, vcc
	v_fma_f32 v24, v24, s97, -v30
	v_mul_f32_e32 v30, 0x3e000000, v25
	v_add_u32_e32 v52, 17, v29
	v_cmp_lt_u32_e64 s[10:11], v52, v33
	v_max_f32_e32 v52, 0, v30
	v_mul_f32_e64 v30, |v30|, s83
	v_exp_f32_e32 v30, v30
	s_nop 0
	v_add_f32_e32 v30, 1.0, v30
	v_cmp_gt_f32_e64 s[12:13], s93, v30
	s_nop 1
	v_cndmask_b32_e64 v53, 0, 32, s[12:13]
	v_ldexp_f32 v30, v30, v53
	v_log_f32_e32 v30, v30
	s_nop 0
	v_mul_f32_e32 v53, 0x3f317217, v30
	v_fma_f32 v53, v30, s96, -v53
	v_fmac_f32_e32 v53, 0x3377d1cf, v30
	v_fmac_f32_e32 v53, 0x3f317217, v30
	v_cmp_lt_f32_e64 s[14:15], |v30|, s77
	s_nop 1
	v_cndmask_b32_e64 v30, v30, v53, s[14:15]
	v_cndmask_b32_e64 v53, 0, v224, s[12:13]
	v_sub_f32_e32 v30, v30, v53
	v_add_f32_e32 v30, v52, v30
	v_cndmask_b32_e64 v52, 0, -v30, s[10:11]
	v_fma_f32 v25, v25, s97, -v30
	v_mul_f32_e32 v30, 0x3e000000, v26
	v_add_u32_e32 v53, 18, v29
	v_cmp_lt_u32_e64 s[12:13], v53, v33
	v_max_f32_e32 v53, 0, v30
	v_mul_f32_e64 v30, |v30|, s83
	v_exp_f32_e32 v30, v30
	s_nop 0
	v_add_f32_e32 v30, 1.0, v30
	v_cmp_gt_f32_e64 s[14:15], s93, v30
	s_nop 1
	v_cndmask_b32_e64 v54, 0, 32, s[14:15]
	v_ldexp_f32 v30, v30, v54
	v_log_f32_e32 v30, v30
	s_nop 0
	v_mul_f32_e32 v54, 0x3f317217, v30
	v_fma_f32 v54, v30, s96, -v54
	v_fmac_f32_e32 v54, 0x3377d1cf, v30
	v_fmac_f32_e32 v54, 0x3f317217, v30
	v_cmp_lt_f32_e64 s[16:17], |v30|, s77
	s_nop 1
	v_cndmask_b32_e64 v30, v30, v54, s[16:17]
	v_cndmask_b32_e64 v54, 0, v224, s[14:15]
	v_sub_f32_e32 v30, v30, v54
	v_add_f32_e32 v30, v53, v30
	v_cndmask_b32_e64 v53, 0, -v30, s[12:13]
	v_fma_f32 v26, v26, s97, -v30
	v_mul_f32_e32 v30, 0x3e000000, v27
	v_add_u32_e32 v54, 19, v29
	v_cmp_lt_u32_e64 s[14:15], v54, v33
	v_max_f32_e32 v54, 0, v30
	v_mul_f32_e64 v30, |v30|, s83
	v_exp_f32_e32 v30, v30
	s_nop 0
	v_add_f32_e32 v30, 1.0, v30
	v_cmp_gt_f32_e64 s[16:17], s93, v30
	s_nop 1
	v_cndmask_b32_e64 v55, 0, 32, s[16:17]
	v_ldexp_f32 v30, v30, v55
	v_log_f32_e32 v30, v30
	s_nop 0
	v_mul_f32_e32 v55, 0x3f317217, v30
	v_fma_f32 v55, v30, s96, -v55
	v_fmac_f32_e32 v55, 0x3377d1cf, v30
	v_fmac_f32_e32 v55, 0x3f317217, v30
	v_cmp_lt_f32_e64 s[18:19], |v30|, s77
	s_nop 1
	v_cndmask_b32_e64 v30, v30, v55, s[18:19]
	v_cndmask_b32_e64 v55, 0, v224, s[16:17]
	v_sub_f32_e32 v30, v30, v55
	v_add_f32_e32 v30, v54, v30
	v_cndmask_b32_e64 v55, 0, -v30, s[14:15]
	v_add_f32_e32 v54, v55, v53
	v_add_f32_e32 v52, v52, v54
	v_fma_f32 v27, v27, s97, -v30
	v_add_f32_e32 v30, v31, v52
	ds_bpermute_b32 v31, v35, v30
	ds_bpermute_b32 v53, v37, v30
	ds_bpermute_b32 v56, v50, v30
	s_waitcnt lgkmcnt(2)
	v_cndmask_b32_e64 v31, v31, 0, s[4:5]
	s_waitcnt lgkmcnt(1)
	v_cndmask_b32_e64 v53, 0, v53, s[6:7]
	v_add_f32_e32 v31, v31, v53
	s_waitcnt lgkmcnt(0)
	v_cndmask_b32_e64 v53, 0, v56, s[8:9]
	v_add_f32_e32 v31, v31, v53
	v_add_f32_e32 v30, v31, v30
	v_add_f32_e32 v31, v28, v31
	v_add_f32_e32 v24, v31, v24
	v_add_f32_e32 v24, v24, v52
	v_mul_f32_e32 v24, 0x3fb8aa3b, v24
	v_exp_f32_e32 v24, v24
	ds_bpermute_b32 v30, v51, v30
	v_cndmask_b32_e32 v53, 0, v24, vcc
	v_add_f32_e32 v24, v31, v25
	v_add_f32_e32 v24, v54, v24
	v_mul_f32_e32 v24, 0x3fb8aa3b, v24
	v_exp_f32_e32 v24, v24
	v_cmp_lt_u32_e32 vcc, v29, v33
	v_cndmask_b32_e64 v54, 0, v24, s[10:11]
	v_add_f32_e32 v24, v31, v26
	v_add_f32_e32 v24, v55, v24
	v_mul_f32_e32 v24, 0x3fb8aa3b, v24
	v_exp_f32_e32 v24, v24
	s_nop 0
	v_cndmask_b32_e64 v55, 0, v24, s[12:13]
	v_add_f32_e32 v24, v31, v27
	v_mul_f32_e32 v24, 0x3fb8aa3b, v24
	v_exp_f32_e32 v24, v24
	s_nop 0
	v_cndmask_b32_e64 v56, 0, v24, s[14:15]
	s_waitcnt vmcnt(8)
	v_mfma_f32_16x16x32_bf16 v[24:27], v[96:99], v[16:19], 0
	v_mfma_f32_16x16x32_bf16 v[24:27], v[58:61], v[20:23], v[24:27]
	s_nop 7
	v_mul_f32_e32 v31, 0x3e000000, v24
	v_max_f32_e32 v48, 0, v31
	v_mul_f32_e64 v31, |v31|, s83
	v_exp_f32_e32 v31, v31
	s_nop 0
	v_add_f32_e32 v31, 1.0, v31
	v_cmp_gt_f32_e64 s[10:11], s93, v31
	s_nop 1
	v_cndmask_b32_e64 v49, 0, 32, s[10:11]
	v_ldexp_f32 v31, v31, v49
	v_log_f32_e32 v31, v31
	s_nop 0
	v_mul_f32_e32 v49, 0x3f317217, v31
	v_fma_f32 v49, v31, s96, -v49
	v_fmac_f32_e32 v49, 0x3377d1cf, v31
	v_fmac_f32_e32 v49, 0x3f317217, v31
	v_cmp_lt_f32_e64 s[12:13], |v31|, s77
	s_nop 1
	v_cndmask_b32_e64 v31, v31, v49, s[12:13]
	v_cndmask_b32_e64 v49, 0, v224, s[10:11]
	v_sub_f32_e32 v31, v31, v49
	v_add_f32_e32 v48, v48, v31
	v_cndmask_b32_e64 v31, 0, -v48, vcc
	v_fma_f32 v24, v24, s97, -v48
	v_mul_f32_e32 v48, 0x3e000000, v25
	v_add_u32_e32 v49, 1, v29
	v_cmp_lt_u32_e64 s[10:11], v49, v33
	v_max_f32_e32 v49, 0, v48
	v_mul_f32_e64 v48, |v48|, s83
	v_exp_f32_e32 v48, v48
	s_nop 0
	v_add_f32_e32 v48, 1.0, v48
	v_cmp_gt_f32_e64 s[12:13], s93, v48
	s_nop 1
	v_cndmask_b32_e64 v52, 0, 32, s[12:13]
	v_ldexp_f32 v48, v48, v52
	v_log_f32_e32 v48, v48
	s_nop 0
	v_mul_f32_e32 v52, 0x3f317217, v48
	v_fma_f32 v52, v48, s96, -v52
	v_fmac_f32_e32 v52, 0x3377d1cf, v48
	v_fmac_f32_e32 v52, 0x3f317217, v48
	v_cmp_lt_f32_e64 s[14:15], |v48|, s77
	s_nop 1
	v_cndmask_b32_e64 v48, v48, v52, s[14:15]
	v_cndmask_b32_e64 v52, 0, v224, s[12:13]
	v_sub_f32_e32 v48, v48, v52
	v_add_f32_e32 v48, v49, v48
	v_cndmask_b32_e64 v49, 0, -v48, s[10:11]
	v_fma_f32 v25, v25, s97, -v48
	v_mul_f32_e32 v48, 0x3e000000, v26
	v_add_u32_e32 v52, 2, v29
	v_cmp_lt_u32_e64 s[12:13], v52, v33
	v_max_f32_e32 v52, 0, v48
	v_mul_f32_e64 v48, |v48|, s83
	v_exp_f32_e32 v48, v48
	v_add_u32_e32 v29, 3, v29
	v_add_f32_e32 v48, 1.0, v48
	v_cmp_gt_f32_e64 s[14:15], s93, v48
	s_nop 1
	v_cndmask_b32_e64 v57, 0, 32, s[14:15]
	v_ldexp_f32 v48, v48, v57
	v_log_f32_e32 v48, v48
	s_nop 0
	v_mul_f32_e32 v57, 0x3f317217, v48
	v_fma_f32 v57, v48, s96, -v57
	v_fmac_f32_e32 v57, 0x3377d1cf, v48
	v_fmac_f32_e32 v57, 0x3f317217, v48
	v_cmp_lt_f32_e64 s[16:17], |v48|, s77
	s_nop 1
	v_cndmask_b32_e64 v48, v48, v57, s[16:17]
	v_cndmask_b32_e64 v57, 0, v224, s[14:15]
	v_sub_f32_e32 v48, v48, v57
	v_add_f32_e32 v48, v52, v48
	v_cndmask_b32_e64 v52, 0, -v48, s[12:13]
	v_fma_f32 v26, v26, s97, -v48
	v_mul_f32_e32 v48, 0x3e000000, v27
	v_cmp_lt_u32_e64 s[14:15], v29, v33
	v_max_f32_e32 v29, 0, v48
	v_mul_f32_e64 v48, |v48|, s83
	v_exp_f32_e32 v48, v48
	s_nop 0
	v_add_f32_e32 v48, 1.0, v48
	v_cmp_gt_f32_e64 s[16:17], s93, v48
	s_nop 1
	v_cndmask_b32_e64 v57, 0, 32, s[16:17]
	v_ldexp_f32 v48, v48, v57
	v_log_f32_e32 v48, v48
	s_nop 0
	v_mul_f32_e32 v57, 0x3f317217, v48
	v_fma_f32 v57, v48, s96, -v57
	v_fmac_f32_e32 v57, 0x3377d1cf, v48
	v_fmac_f32_e32 v57, 0x3f317217, v48
	v_cmp_lt_f32_e64 s[18:19], |v48|, s77
	s_nop 1
	v_cndmask_b32_e64 v48, v48, v57, s[18:19]
	v_cndmask_b32_e64 v57, 0, v224, s[16:17]
	v_sub_f32_e32 v48, v48, v57
	v_add_f32_e32 v29, v29, v48
	v_cndmask_b32_e64 v57, 0, -v29, s[14:15]
	v_add_f32_e32 v58, v57, v52
	v_add_f32_e32 v59, v49, v58
	v_add_f32_e32 v52, v31, v59
	v_fma_f32 v27, v27, s97, -v29
	ds_bpermute_b32 v29, v35, v52
	ds_bpermute_b32 v31, v37, v52
	ds_bpermute_b32 v48, v50, v52
	s_waitcnt lgkmcnt(2)
	v_cndmask_b32_e64 v29, v29, 0, s[4:5]
	s_waitcnt lgkmcnt(1)
	v_cndmask_b32_e64 v31, 0, v31, s[6:7]
	v_add_f32_e32 v29, v29, v31
	s_waitcnt lgkmcnt(0)
	v_cndmask_b32_e64 v31, 0, v48, s[8:9]
	v_pk_add_f32 v[48:49], v[28:29], v[30:31]
	s_nop 0
	v_add_f32_e32 v28, v49, v52
	ds_bpermute_b32 v52, v51, v28
	v_add_f32_e32 v28, v48, v49
	v_add_f32_e32 v24, v28, v24
	v_add_f32_e32 v25, v28, v25
	v_add_f32_e32 v26, v28, v26
	v_add_f32_e32 v24, v24, v59
	v_add_f32_e32 v25, v58, v25
	v_add_f32_e32 v26, v57, v26
	v_add_f32_e32 v27, v28, v27
	v_mul_f32_e32 v24, 0x3fb8aa3b, v24
	v_mul_f32_e32 v25, 0x3fb8aa3b, v25
	v_mul_f32_e32 v26, 0x3fb8aa3b, v26
	v_mul_f32_e32 v27, 0x3fb8aa3b, v27
	v_exp_f32_e32 v24, v24
	v_exp_f32_e32 v25, v25
	v_exp_f32_e32 v26, v26
	v_exp_f32_e32 v27, v27
	v_cndmask_b32_e32 v24, 0, v24, vcc
	v_cndmask_b32_e64 v25, 0, v25, s[10:11]
	v_cndmask_b32_e64 v26, 0, v26, s[12:13]
	v_cndmask_b32_e64 v27, 0, v27, s[14:15]
	v_cvt_pk_bf16_f32 v24, v24, v25
	v_cvt_pk_bf16_f32 v25, v26, v27
	v_cvt_pk_bf16_f32 v26, v53, v54
	v_cvt_pk_bf16_f32 v27, v55, v56
	s_mov_b32 s10, 0xc2b40000
	s_nop 1
	s_waitcnt vmcnt(6)
	v_mfma_f32_16x16x32_bf16 v[12:15], v[100:103], v[24:27], v[12:15]
	s_waitcnt vmcnt(4)
	v_mfma_f32_16x16x32_bf16 v[8:11], v[104:107], v[24:27], v[8:11]
	s_waitcnt vmcnt(2)
	v_mfma_f32_16x16x32_bf16 v[4:7], v[108:111], v[24:27], v[4:7]
	s_waitcnt vmcnt(0)
	v_mfma_f32_16x16x32_bf16 v[0:3], v[112:115], v[24:27], v[0:3]
	s_waitcnt lgkmcnt(0)
	v_add_f32_e32 v28, v48, v52
	v_cmp_gt_f32_e32 vcc, s10, v28
	s_cmp_lg_u64 vcc, exec
	s_cselect_b64 s[10:11], -1, 0
	s_cmp_lg_u32 s58, 0
	s_cselect_b64 s[12:13], -1, 0
	s_and_b64 s[10:11], s[12:13], s[10:11]
	s_sub_i32 s58, s58, 32
	s_and_b64 vcc, exec, s[10:11]
	s_cbranch_vccnz .LBB0_844
	v_pk_mul_f32 v[16:17], v[14:15], v[14:15]
	v_pk_mul_f32 v[18:19], v[12:13], v[12:13]
	v_lshlrev_b32_e32 v156, 1, v36
	v_pk_mov_b32 v[20:21], v[18:19], v[16:17] op_sel:[1,0]
	v_mov_b32_e32 v19, v17
	v_pk_add_f32 v[16:17], v[20:21], v[18:19]
	v_pk_mul_f32 v[18:19], v[10:11], v[10:11]
	v_pk_mul_f32 v[20:21], v[8:9], v[8:9]
	v_pk_add_f32 v[16:17], v[16:17], v[16:17] op_sel:[0,1] op_sel_hi:[1,0]
	v_pk_mov_b32 v[22:23], v[20:21], v[18:19] op_sel:[1,0]
	v_mov_b32_e32 v21, v19
	v_pk_add_f32 v[18:19], v[22:23], v[20:21]
	v_mul_f32_e32 v20, v0, v0
	v_mul_f32_e32 v21, v1, v1
	v_pk_add_f32 v[18:19], v[18:19], v[18:19] op_sel:[0,1] op_sel_hi:[1,0]
	v_mov_b32_e32 v17, v20
	v_mov_b32_e32 v19, v21
	v_pk_add_f32 v[16:17], v[16:17], v[18:19]
	v_mul_f32_e32 v18, v5, v5
	v_mul_f32_e32 v20, v7, v7
	v_mul_f32_e32 v22, v2, v2
	v_mul_f32_e32 v23, v3, v3
	v_pk_fma_f32 v[18:19], v[4:5], v[4:5], v[18:19] op_sel_hi:[1,1,0]
	v_pk_fma_f32 v[20:21], v[6:7], v[6:7], v[20:21] op_sel_hi:[1,1,0]
	v_mov_b32_e32 v19, v22
	v_mov_b32_e32 v21, v23
	v_pk_add_f32 v[18:19], v[18:19], v[20:21]
	global_load_dwordx4 v[20:23], v[40:41], off
	v_pk_add_f32 v[16:17], v[16:17], v[18:19]
	v_and_b32_e32 v18, 64, v217
	v_add_f32_e32 v16, v16, v17
	v_xor_b32_e32 v17, 16, v217
	v_add_u32_e32 v18, 64, v18
	v_cmp_lt_i32_e32 vcc, v17, v18
	s_mov_b64 s[10:11], 0
	s_nop 0
	v_cndmask_b32_e32 v17, v217, v17, vcc
	v_lshlrev_b32_e32 v17, 2, v17
	ds_bpermute_b32 v17, v17, v16
	s_waitcnt lgkmcnt(0)
	v_add_f32_e32 v16, v16, v17
	v_xor_b32_e32 v17, 32, v217
	v_cmp_lt_i32_e32 vcc, v17, v18
	s_nop 1
	v_cndmask_b32_e32 v17, v217, v17, vcc
	v_lshlrev_b32_e32 v17, 2, v17
	ds_bpermute_b32 v17, v17, v16
	s_waitcnt lgkmcnt(0)
	v_add_f32_e32 v16, v16, v17
	v_fmamk_f32 v16, v16, 0x3c800000, v212
	v_rsq_f32_e32 v18, v16
	v_lshlrev_b64 v[16:17], 11, v[42:43]
	v_lshl_add_u64 v[16:17], s[36:37], 0, v[16:17]
	v_lshl_add_u64 v[16:17], v[16:17], 0, s[44:45]
	v_pk_mul_f32 v[12:13], v[12:13], v[18:19] op_sel_hi:[1,0]
	v_pk_mul_f32 v[14:15], v[14:15], v[18:19] op_sel_hi:[1,0]
	v_lshl_add_u64 v[16:17], v[16:17], 0, v[156:157]
	v_pk_mul_f32 v[8:9], v[8:9], v[18:19] op_sel_hi:[1,0]
	v_pk_mul_f32 v[10:11], v[10:11], v[18:19] op_sel_hi:[1,0]
	v_pk_mul_f32 v[4:5], v[4:5], v[18:19] op_sel_hi:[1,0]
	v_pk_mul_f32 v[6:7], v[6:7], v[18:19] op_sel_hi:[1,0]
	v_pk_mul_f32 v[0:1], v[0:1], v[18:19] op_sel_hi:[1,0]
	v_pk_mul_f32 v[2:3], v[2:3], v[18:19] op_sel_hi:[1,0]
	s_waitcnt vmcnt(0)
	v_pk_mul_f32 v[12:13], v[20:21], v[12:13]
	v_pk_mul_f32 v[14:15], v[22:23], v[14:15]
	v_cvt_pk_bf16_f32 v12, v12, v13
	v_cvt_pk_bf16_f32 v13, v14, v15
	global_store_dwordx2 v[16:17], v[12:13], off
	global_load_dwordx4 v[12:15], v[40:41], off offset:64
	s_waitcnt vmcnt(0)
	v_pk_mul_f32 v[8:9], v[12:13], v[8:9]
	v_pk_mul_f32 v[10:11], v[14:15], v[10:11]
	v_cvt_pk_bf16_f32 v8, v8, v9
	v_cvt_pk_bf16_f32 v9, v10, v11
	global_store_dwordx2 v[16:17], v[8:9], off offset:32
	global_load_dwordx4 v[8:11], v[40:41], off offset:128
	s_waitcnt vmcnt(0)
	v_pk_mul_f32 v[4:5], v[4:5], v[8:9]
	v_pk_mul_f32 v[6:7], v[6:7], v[10:11]
	v_cvt_pk_bf16_f32 v4, v4, v5
	v_cvt_pk_bf16_f32 v5, v6, v7
	global_store_dwordx2 v[16:17], v[4:5], off offset:64
	global_load_dwordx4 v[4:7], v[40:41], off offset:192
	s_waitcnt vmcnt(0)
	v_pk_mul_f32 v[0:1], v[0:1], v[4:5]
	v_pk_mul_f32 v[2:3], v[2:3], v[6:7]
	v_cvt_pk_bf16_f32 v0, v0, v1
	v_cvt_pk_bf16_f32 v1, v2, v3
	global_store_dwordx2 v[16:17], v[0:1], off offset:96
	s_branch .LBB0_837
